# v8 + GEMM prologue de-serialised: K-tile 1 staging loads issued before the first wait (vmcnt 8)
# baseline (speedup 1.0000x reference)
; #define PG8_STAGE(bufoff, gbase, voff) do { _Pragma("unroll") for (int _i = 0; _i < 2; ++_i) \
;         __builtin_amdgcn_global_load_lds((const unsigned*)((const char*)(gbase) + (voff)[_i]), (PG8_LAS unsigned*)(lds + (bufoff) + ldsw + _i * 8192), 16, 0, 0); } while (0)
; #define PG8_WAIT_V(n) asm volatile("s_waitcnt vmcnt(" #n ")" ::: "memory")
; #define PG8_BAR __builtin_amdgcn_s_barrier()
; template <class Epi, class Sched, bool ALIGN_EPI = false, bool SP2 = false>
; __device__ __forceinline__ void gemm_phase(PG8_LAS unsigned char* lds, const Gemm g, const Sched& S, const Epi& E, const int tid) {
;     ...
;     if constexpr (SP2) {
;         PG8_STAGE(PG8_SB(0, 0), cB, voffB); PG8_STAGE(PG8_SB(0, 1), cB + hstep, voffB); PG8_STAGE(PG8_SA(0, 0), cA, voffA); PG8_STAGE(PG8_SA(0, 1), cA + hstep, voffA);
;         if (wr == 1) PG8_BAR;
;         PG8_WAIT_V(2); PG8_BAR;
;         PG8_STAGE(PG8_SB(1, 0), cB + kstep, voffB); PG8_STAGE(PG8_SA(1, 0), cA + kstep, voffA); PG8_STAGE(PG8_SB(1, 1), cB + hstep + kstep, voffB);
;         PG8_WAIT_V(6); PG8_BAR;
.LBB0_196:
	s_andn2_b64 vcc, exec, s[8:9]
	s_cbranch_vccnz .LBB0_161
	s_lshl_b32 s82, s22, 8
	s_mov_b32 s83, s89
	s_lshl_b64 s[16:17], s[82:83], 1
	s_ashr_i32 s12, s92, 31
	s_mul_i32 s12, s16, s12
	s_mul_hi_u32 s13, s16, s92
	s_add_i32 s12, s13, s12
	s_bfe_u32 s13, s22, 0x10017
	s_mul_i32 s19, s13, s92
	s_add_i32 s19, s12, s19
	s_ashr_i32 s12, s47, 31
	s_mul_i32 s12, s16, s12
	s_mul_hi_u32 s24, s16, s47
	s_ashr_i32 s8, s18, 6
	s_add_i32 s12, s24, s12
	s_mul_i32 s13, s13, s47
	s_ashr_i32 s9, s18, 8
	s_lshl_b32 s75, s8, 10
	s_add_i32 s13, s12, s13
	s_mul_i32 s12, s16, s47
	v_mul_lo_u32 v2, s22, v170
	s_add_u32 s12, s52, s12
	v_add_lshl_u32 v146, v2, v171, 1
	v_mul_lo_u32 v2, s22, v172
	s_addc_u32 s13, s53, s13
	s_add_i32 s78, s75, 0
	v_add_lshl_u32 v148, v2, v171, 1
	v_mul_lo_u32 v2, s22, v173
	s_add_i32 m0, s78, 0x10000
	v_add_lshl_u32 v150, v2, v174, 1
	v_mul_lo_u32 v2, s22, v175
	global_load_lds_dwordx4 v148, s[12:13]
	s_add_i32 m0, s78, 0x12000
	v_add_lshl_u32 v152, v2, v174, 1
	s_add_u32 s24, s12, s82
	global_load_lds_dwordx4 v152, s[12:13]
	s_addc_u32 s25, s13, 0
	s_add_i32 m0, s78, 0x14000
	s_mul_i32 s23, s16, s92
	global_load_lds_dwordx4 v148, s[24:25]
	s_add_i32 m0, s78, 0x16000
	s_add_u32 s76, s56, s23
	v_mov_b32_e32 v149, v193
	v_mov_b32_e32 v153, v193
	s_addc_u32 s77, s57, s19
	s_add_i32 s79, s78, 0x2000
	v_lshl_add_u64 v[6:7], s[24:25], 0, v[148:149]
	v_lshl_add_u64 v[8:9], s[24:25], 0, v[152:153]
	global_load_lds_dwordx4 v152, s[24:25]
	s_mov_b32 m0, s78
	s_add_u32 s24, s76, s82
	global_load_lds_dwordx4 v146, s[76:77]
	s_mov_b32 m0, s79
	s_addc_u32 s25, s77, 0
	s_add_i32 s36, s78, 0x4000
	global_load_lds_dwordx4 v150, s[76:77]
	s_mov_b32 m0, s36
	s_add_i32 s37, s78, 0x6000
	global_load_lds_dwordx4 v146, s[24:25]
	s_mov_b32 m0, s37
	v_mov_b32_e32 v147, v193
	global_load_lds_dwordx4 v150, s[24:25]
	v_mov_b32_e32 v151, v193
	s_cmp_eq_u32 s9, 1
	v_lshl_add_u64 v[2:3], s[12:13], 0, v[148:149]
	v_lshl_add_u64 v[4:5], s[12:13], 0, v[152:153]
	v_lshl_add_u64 v[10:11], s[76:77], 0, v[146:147]
	v_lshl_add_u64 v[12:13], s[76:77], 0, v[150:151]
	s_cselect_b64 s[42:43], -1, 0
	s_add_i32 m0, s78, 0x18000
	v_lshl_add_u64 v[2:3], v[2:3], 0, s[90:91]
	global_load_lds_dwordx4 v[2:3], off
	v_lshl_add_u64 v[2:3], v[4:5], 0, s[90:91]
	s_add_i32 m0, s78, 0x1a000
	s_add_i32 s40, s78, 0x8000
	global_load_lds_dwordx4 v[2:3], off
	v_lshl_add_u64 v[2:3], v[10:11], 0, s[90:91]
	s_mov_b32 m0, s40
	s_add_i32 s41, s78, 0xa000
	global_load_lds_dwordx4 v[2:3], off
	v_lshl_add_u64 v[2:3], v[12:13], 0, s[90:91]
	s_mov_b32 m0, s41
	v_lshlrev_b32_e32 v15, 2, v176
	global_load_lds_dwordx4 v[2:3], off
	s_add_i32 m0, s78, 0x1c000
	v_lshl_add_u64 v[2:3], v[6:7], 0, s[90:91]
	global_load_lds_dwordx4 v[2:3], off
	v_lshl_add_u64 v[2:3], v[8:9], 0, s[90:91]
	s_add_i32 m0, s78, 0x1e000
	s_and_b32 s38, s8, 3
	global_load_lds_dwordx4 v[2:3], off
	s_cmp_lg_u32 s9, 1
	s_cbranch_scc1 .LBB0_199
	s_barrier
.LBB0_199:
	s_waitcnt vmcnt(8)
	s_barrier
	s_lshr_b32 s84, s22, 6
	v_lshl_or_b32 v14, v176, 6, v177
	s_lshl_b32 s8, s9, 13
	v_and_b32_e32 v15, 32, v15
	v_bitop3_b32 v14, v14, s8, v15 bitop3:0xde
	s_lshl_b32 s8, s38, 5
	s_add_i32 s39, s84, -2
	s_cmpk_lt_u32 s18, 0x100
	s_cselect_b64 s[22:23], -1, 0
	s_lshl_b32 s18, s5, 2
	v_cvt_f32_u32_e32 v3, s18
	v_lshl_or_b32 v179, s9, 6, v176
	s_lshl_b32 s9, s38, 6
	s_and_b32 s19, s9, 0x80
	v_rcp_iflag_f32_e32 v3, v3
	s_lshl_b32 s85, s5, 3
	s_cmp_lg_u64 s[58:59], 0
	s_cselect_b64 s[24:25], -1, 0
	v_mul_f32_e32 v3, 0x4f7ffffe, v3
	s_cmp_lg_u64 s[10:11], 0
	v_cvt_u32_f32_e32 v3, v3
	v_lshlrev_b32_e32 v154, 2, v0
	v_mov_b32_e32 v155, v193
	s_cselect_b64 s[26:27], -1, 0
	s_cmp_lg_u64 s[20:21], 0
	v_lshl_add_u64 v[156:157], s[0:1], 0, v[154:155]
	s_cselect_b64 s[0:1], -1, 0
	v_writelane_b32 v255, s0, 17
	s_waitcnt vmcnt(6)
	v_and_or_b32 v2, s8, 32, v0
	v_lshlrev_b32_e32 v192, 3, v2
	v_writelane_b32 v255, s1, 18
	s_sub_i32 s0, 0, s18
	v_readfirstlane_b32 s1, v3
	s_mul_i32 s0, s0, s1
	v_or_b32_e32 v2, s19, v2
	s_mul_hi_u32 s0, s1, s0
	v_lshl_or_b32 v180, s38, 12, v178
	s_mov_b32 s45, s89
	v_lshl_add_u64 v[158:159], s[10:11], 0, v[192:193]
	s_mov_b32 s73, s72
	v_or_b32_e32 v155, s8, v0
	s_mov_b32 s19, 0
	s_add_i32 s46, s1, s0
	v_lshl_add_u64 v[160:161], s[82:83], 0, v[146:147]
	v_lshl_add_u64 v[162:163], s[82:83], 0, v[150:151]
	v_add_u32_e32 v181, 0, v14
	v_lshlrev_b32_e32 v182, 1, v2
	s_lshl_b32 s88, s9, 1
	s_barrier
	s_branch .LBB0_202
